# h1/h3 serial loops: the 8-step body's LDS reads issued together at the top (one lgkmcnt wait per 8 steps)
# speedup vs baseline: 1.1383x; 1.0014x over previous
; DEVI float b2f(bfu b) { return __uint_as_float(((unsigned)b) << 16); }
; DEVI float sigmoidf_(float x) { return 1.f / (1.f + __expf(-x)); }
; DEVI void h1_item(const Params& P, int l, int ck, int h, char* smem, int tid) {
;     ...
; #pragma unroll 8
;   for (int i = 0; i < Lh; ++i) {
;     float f = lb + (1.f - lb) * sigmoidf_(b2f(FS[(hf * Lh + i) * 136 + d]));
;     tot += __logf(f);
;   }
.LBB0_397:
	ds_read_u16 v208, v0
	ds_read_u16 v209, v0 offset:272
	ds_read_u16 v210, v0 offset:544
	ds_read_u16 v211, v0 offset:816
	ds_read_u16 v212, v0 offset:1088
	ds_read_u16 v213, v0 offset:1360
	ds_read_u16 v214, v0 offset:1632
	ds_read_u16 v215, v0 offset:1904
	s_waitcnt lgkmcnt(0)
	v_mov_b32_e32 v2, v208
	s_add_i32 s26, s26, -8
	s_cmp_eq_u32 s26, 0
	v_lshlrev_b32_e32 v2, 16, v2
	v_mul_f32_e32 v2, 0xbfb8aa3b, v2
	v_exp_f32_e32 v2, v2
	s_nop 0
	v_add_f32_e32 v2, 1.0, v2
	v_div_scale_f32 v3, s[42:43], v2, v2, 1.0
	v_rcp_f32_e32 v5, v3
	s_nop 0
	v_fma_f32 v6, -v3, v5, 1.0
	v_fmac_f32_e32 v5, v6, v5
	v_div_scale_f32 v6, vcc, 1.0, v2, 1.0
	v_mul_f32_e32 v7, v6, v5
	v_fma_f32 v8, -v3, v7, v6
	v_fmac_f32_e32 v7, v8, v5
	v_fma_f32 v3, -v3, v7, v6
	v_div_fmas_f32 v3, v3, v5, v7
	v_div_fixup_f32 v2, v3, v2, 1.0
	v_fma_f32 v2, v4, v2, v20
	v_cmp_gt_f32_e32 vcc, s34, v2
	s_nop 1
	v_cndmask_b32_e64 v3, 0, 32, vcc
	v_ldexp_f32 v2, v2, v3
	v_log_f32_e32 v2, v2
	s_nop 0
	v_mul_f32_e32 v3, 0x3f317217, v2
	v_fma_f32 v3, v2, s38, -v3
	v_fmac_f32_e32 v3, 0x3377d1cf, v2
	v_fmac_f32_e32 v3, 0x3f317217, v2
	v_cmp_lt_f32_e64 s[42:43], |v2|, s20
	s_nop 1
	v_cndmask_b32_e64 v2, v2, v3, s[42:43]
	v_cndmask_b32_e32 v3, 0, v193, vcc
	v_sub_f32_e32 v2, v2, v3
	v_add_f32_e32 v1, v1, v2
	v_mov_b32_e32 v2, v209
	v_lshlrev_b32_e32 v2, 16, v2
	v_mul_f32_e32 v2, 0xbfb8aa3b, v2
	v_exp_f32_e32 v2, v2
	s_nop 0
	v_add_f32_e32 v2, 1.0, v2
	v_div_scale_f32 v3, s[42:43], v2, v2, 1.0
	v_rcp_f32_e32 v5, v3
	s_nop 0
	v_fma_f32 v6, -v3, v5, 1.0
	v_fmac_f32_e32 v5, v6, v5
	v_div_scale_f32 v6, vcc, 1.0, v2, 1.0
	v_mul_f32_e32 v7, v6, v5
	v_fma_f32 v8, -v3, v7, v6
	v_fmac_f32_e32 v7, v8, v5
	v_fma_f32 v3, -v3, v7, v6
	v_div_fmas_f32 v3, v3, v5, v7
	v_div_fixup_f32 v2, v3, v2, 1.0
	v_fma_f32 v2, v4, v2, v20
	v_cmp_gt_f32_e32 vcc, s34, v2
	s_nop 1
	v_cndmask_b32_e64 v3, 0, 32, vcc
	v_ldexp_f32 v2, v2, v3
	v_log_f32_e32 v2, v2
	s_nop 0
	v_mul_f32_e32 v3, 0x3f317217, v2
	v_fma_f32 v3, v2, s38, -v3
	v_fmac_f32_e32 v3, 0x3377d1cf, v2
	v_fmac_f32_e32 v3, 0x3f317217, v2
	v_cmp_lt_f32_e64 s[42:43], |v2|, s20
	s_nop 1
	v_cndmask_b32_e64 v2, v2, v3, s[42:43]
	v_cndmask_b32_e32 v3, 0, v193, vcc
	v_sub_f32_e32 v2, v2, v3
	v_add_f32_e32 v1, v1, v2
	v_mov_b32_e32 v2, v210
	v_lshlrev_b32_e32 v2, 16, v2
	v_mul_f32_e32 v2, 0xbfb8aa3b, v2
	v_exp_f32_e32 v2, v2
	s_nop 0
	v_add_f32_e32 v2, 1.0, v2
	v_div_scale_f32 v3, s[42:43], v2, v2, 1.0
	v_rcp_f32_e32 v5, v3
	s_nop 0
	v_fma_f32 v6, -v3, v5, 1.0
	v_fmac_f32_e32 v5, v6, v5
	v_div_scale_f32 v6, vcc, 1.0, v2, 1.0
	v_mul_f32_e32 v7, v6, v5
	v_fma_f32 v8, -v3, v7, v6
	v_fmac_f32_e32 v7, v8, v5
	v_fma_f32 v3, -v3, v7, v6
	v_div_fmas_f32 v3, v3, v5, v7
	v_div_fixup_f32 v2, v3, v2, 1.0
	v_fma_f32 v2, v4, v2, v20
	v_cmp_gt_f32_e32 vcc, s34, v2
	s_nop 1
	v_cndmask_b32_e64 v3, 0, 32, vcc
	v_ldexp_f32 v2, v2, v3
	v_log_f32_e32 v2, v2
	s_nop 0
	v_mul_f32_e32 v3, 0x3f317217, v2
	v_fma_f32 v3, v2, s38, -v3
	v_fmac_f32_e32 v3, 0x3377d1cf, v2
	v_fmac_f32_e32 v3, 0x3f317217, v2
	v_cmp_lt_f32_e64 s[42:43], |v2|, s20
	s_nop 1
	v_cndmask_b32_e64 v2, v2, v3, s[42:43]
	v_cndmask_b32_e32 v3, 0, v193, vcc
	v_sub_f32_e32 v2, v2, v3
	v_add_f32_e32 v1, v1, v2
	v_mov_b32_e32 v2, v211
	v_lshlrev_b32_e32 v2, 16, v2
	v_mul_f32_e32 v2, 0xbfb8aa3b, v2
	v_exp_f32_e32 v2, v2
	s_nop 0
	v_add_f32_e32 v2, 1.0, v2
	v_div_scale_f32 v3, s[42:43], v2, v2, 1.0
	v_rcp_f32_e32 v5, v3
	s_nop 0
	v_fma_f32 v6, -v3, v5, 1.0
	v_fmac_f32_e32 v5, v6, v5
	v_div_scale_f32 v6, vcc, 1.0, v2, 1.0
	v_mul_f32_e32 v7, v6, v5
	v_fma_f32 v8, -v3, v7, v6
	v_fmac_f32_e32 v7, v8, v5
	v_fma_f32 v3, -v3, v7, v6
	v_div_fmas_f32 v3, v3, v5, v7
	v_div_fixup_f32 v2, v3, v2, 1.0
	v_fma_f32 v2, v4, v2, v20
	v_cmp_gt_f32_e32 vcc, s34, v2
	s_nop 1
	v_cndmask_b32_e64 v3, 0, 32, vcc
	v_ldexp_f32 v2, v2, v3
	v_log_f32_e32 v2, v2
	s_nop 0
	v_mul_f32_e32 v3, 0x3f317217, v2
	v_fma_f32 v3, v2, s38, -v3
	v_fmac_f32_e32 v3, 0x3377d1cf, v2
	v_fmac_f32_e32 v3, 0x3f317217, v2
	v_cmp_lt_f32_e64 s[42:43], |v2|, s20
	s_nop 1
	v_cndmask_b32_e64 v2, v2, v3, s[42:43]
	v_cndmask_b32_e32 v3, 0, v193, vcc
	v_sub_f32_e32 v2, v2, v3
	v_add_f32_e32 v1, v1, v2
	v_mov_b32_e32 v2, v212
	v_lshlrev_b32_e32 v2, 16, v2
	v_mul_f32_e32 v2, 0xbfb8aa3b, v2
	v_exp_f32_e32 v2, v2
	s_nop 0
	v_add_f32_e32 v2, 1.0, v2
	v_div_scale_f32 v3, s[42:43], v2, v2, 1.0
	v_rcp_f32_e32 v5, v3
	s_nop 0
	v_fma_f32 v6, -v3, v5, 1.0
	v_fmac_f32_e32 v5, v6, v5
	v_div_scale_f32 v6, vcc, 1.0, v2, 1.0
	v_mul_f32_e32 v7, v6, v5
	v_fma_f32 v8, -v3, v7, v6
	v_fmac_f32_e32 v7, v8, v5
	v_fma_f32 v3, -v3, v7, v6
	v_div_fmas_f32 v3, v3, v5, v7
	v_div_fixup_f32 v2, v3, v2, 1.0
	v_fma_f32 v2, v4, v2, v20
	v_cmp_gt_f32_e32 vcc, s34, v2
	s_nop 1
	v_cndmask_b32_e64 v3, 0, 32, vcc
	v_ldexp_f32 v2, v2, v3
	v_log_f32_e32 v2, v2
	s_nop 0
	v_mul_f32_e32 v3, 0x3f317217, v2
	v_fma_f32 v3, v2, s38, -v3
	v_fmac_f32_e32 v3, 0x3377d1cf, v2
	v_fmac_f32_e32 v3, 0x3f317217, v2
	v_cmp_lt_f32_e64 s[42:43], |v2|, s20
	s_nop 1
	v_cndmask_b32_e64 v2, v2, v3, s[42:43]
	v_cndmask_b32_e32 v3, 0, v193, vcc
	v_sub_f32_e32 v2, v2, v3
	v_add_f32_e32 v1, v1, v2
	v_mov_b32_e32 v2, v213
	v_lshlrev_b32_e32 v2, 16, v2
	v_mul_f32_e32 v2, 0xbfb8aa3b, v2
	v_exp_f32_e32 v2, v2
	s_nop 0
	v_add_f32_e32 v2, 1.0, v2
	v_div_scale_f32 v3, s[42:43], v2, v2, 1.0
	v_rcp_f32_e32 v5, v3
	s_nop 0
	v_fma_f32 v6, -v3, v5, 1.0
	v_fmac_f32_e32 v5, v6, v5
	v_div_scale_f32 v6, vcc, 1.0, v2, 1.0
	v_mul_f32_e32 v7, v6, v5
	v_fma_f32 v8, -v3, v7, v6
	v_fmac_f32_e32 v7, v8, v5
	v_fma_f32 v3, -v3, v7, v6
	v_div_fmas_f32 v3, v3, v5, v7
	v_div_fixup_f32 v2, v3, v2, 1.0
	v_fma_f32 v2, v4, v2, v20
	v_cmp_gt_f32_e32 vcc, s34, v2
	s_nop 1
; DEVI float b2f(bfu b) { return __uint_as_float(((unsigned)b) << 16); }
; DEVI float sigmoidf_(float x) { return 1.f / (1.f + __expf(-x)); }
; DEVI void h1_item(const Params& P, int l, int ck, int h, char* smem, int tid) {
;     ...
; #pragma unroll 8
;   for (int i = 0; i < Lh; ++i) {
;     float f = lb + (1.f - lb) * sigmoidf_(b2f(FS[(hf * Lh + i) * 136 + d]));
;     tot += __logf(f);
;   }
;   tots[hf * 128 + d] = tot;
;   __syncthreads();
;   float run = hf ? 0.f : tots[128 + d];
; #pragma unroll 8
;   for (int i = Lh - 1; i >= 0; --i) {
;     const int sr = hf * Lh + i;
;     float f = lb + (1.f - lb) * sigmoidf_(b2f(FS[sr * 136 + d]));
;     KT[d * 72 + sr] = f2b((1.f - f) * __expf(run));
;     run += __logf(f);
;   }
	v_cndmask_b32_e64 v3, 0, 32, vcc
	v_ldexp_f32 v2, v2, v3
	v_log_f32_e32 v2, v2
	s_nop 0
	v_mul_f32_e32 v3, 0x3f317217, v2
	v_fma_f32 v3, v2, s38, -v3
	v_fmac_f32_e32 v3, 0x3377d1cf, v2
	v_fmac_f32_e32 v3, 0x3f317217, v2
	v_cmp_lt_f32_e64 s[42:43], |v2|, s20
	s_nop 1
	v_cndmask_b32_e64 v2, v2, v3, s[42:43]
	v_cndmask_b32_e32 v3, 0, v193, vcc
	v_sub_f32_e32 v2, v2, v3
	v_add_f32_e32 v1, v1, v2
	v_mov_b32_e32 v2, v214
	v_lshlrev_b32_e32 v2, 16, v2
	v_mul_f32_e32 v2, 0xbfb8aa3b, v2
	v_exp_f32_e32 v2, v2
	s_nop 0
	v_add_f32_e32 v2, 1.0, v2
	v_div_scale_f32 v3, s[42:43], v2, v2, 1.0
	v_rcp_f32_e32 v5, v3
	s_nop 0
	v_fma_f32 v6, -v3, v5, 1.0
	v_fmac_f32_e32 v5, v6, v5
	v_div_scale_f32 v6, vcc, 1.0, v2, 1.0
	v_mul_f32_e32 v7, v6, v5
	v_fma_f32 v8, -v3, v7, v6
	v_fmac_f32_e32 v7, v8, v5
	v_fma_f32 v3, -v3, v7, v6
	v_div_fmas_f32 v3, v3, v5, v7
	v_div_fixup_f32 v2, v3, v2, 1.0
	v_fma_f32 v2, v4, v2, v20
	v_cmp_gt_f32_e32 vcc, s34, v2
	s_nop 1
	v_cndmask_b32_e64 v3, 0, 32, vcc
	v_ldexp_f32 v2, v2, v3
	v_log_f32_e32 v2, v2
	s_nop 0
	v_mul_f32_e32 v3, 0x3f317217, v2
	v_fma_f32 v3, v2, s38, -v3
	v_fmac_f32_e32 v3, 0x3377d1cf, v2
	v_fmac_f32_e32 v3, 0x3f317217, v2
	v_cmp_lt_f32_e64 s[42:43], |v2|, s20
	s_nop 1
	v_cndmask_b32_e64 v2, v2, v3, s[42:43]
	v_cndmask_b32_e32 v3, 0, v193, vcc
	v_sub_f32_e32 v2, v2, v3
	v_add_f32_e32 v1, v1, v2
	v_mov_b32_e32 v2, v215
	v_add_u32_e32 v0, 0x880, v0
	v_lshlrev_b32_e32 v2, 16, v2
	v_mul_f32_e32 v2, 0xbfb8aa3b, v2
	v_exp_f32_e32 v2, v2
	s_nop 0
	v_add_f32_e32 v2, 1.0, v2
	v_div_scale_f32 v3, s[42:43], v2, v2, 1.0
	v_rcp_f32_e32 v5, v3
	s_nop 0
	v_fma_f32 v6, -v3, v5, 1.0
	v_fmac_f32_e32 v5, v6, v5
	v_div_scale_f32 v6, vcc, 1.0, v2, 1.0
	v_mul_f32_e32 v7, v6, v5
	v_fma_f32 v8, -v3, v7, v6
	v_fmac_f32_e32 v7, v8, v5
	v_fma_f32 v3, -v3, v7, v6
	v_div_fmas_f32 v3, v3, v5, v7
	v_div_fixup_f32 v2, v3, v2, 1.0
	v_fma_f32 v2, v4, v2, v20
	v_cmp_gt_f32_e32 vcc, s34, v2
	s_nop 1
	v_cndmask_b32_e64 v3, 0, 32, vcc
	v_ldexp_f32 v2, v2, v3
	v_log_f32_e32 v2, v2
	s_nop 0
	v_mul_f32_e32 v3, 0x3f317217, v2
	v_fma_f32 v3, v2, s38, -v3
	v_fmac_f32_e32 v3, 0x3377d1cf, v2
	v_fmac_f32_e32 v3, 0x3f317217, v2
	v_cmp_lt_f32_e64 s[42:43], |v2|, s20
	s_nop 1
	v_cndmask_b32_e64 v2, v2, v3, s[42:43]
	v_cndmask_b32_e32 v3, 0, v193, vcc
	v_sub_f32_e32 v2, v2, v3
	v_add_f32_e32 v1, v1, v2
	s_cbranch_scc0 .LBB0_397
	v_mov_b32_e32 v5, 0
	ds_write_b32 v100, v1 offset:54272
	s_waitcnt lgkmcnt(0)
	s_barrier
	s_and_saveexec_b64 s[26:27], s[40:41]
	ds_read_b32 v5, v100 offset:54784
	s_or_b64 exec, exec, s[26:27]
	v_mad_u64_u32 v[0:1], s[26:27], v164, s24, v[138:139]
	v_mad_u64_u32 v[2:3], s[26:27], v165, s24, v[140:141]
.LBB0_401:
	ds_read_u16 v208, v0 offset:1904
	ds_read_u16 v209, v0 offset:1632
	ds_read_u16 v210, v0 offset:1360
	ds_read_u16 v211, v0 offset:1088
	ds_read_u16 v212, v0 offset:816
	ds_read_u16 v213, v0 offset:544
	ds_read_u16 v214, v0 offset:272
	ds_read_u16 v215, v0
	s_waitcnt lgkmcnt(0)
	v_mov_b32_e32 v1, v208
	v_mul_f32_e32 v3, 0x3fb8aa3b, v5
	v_exp_f32_e32 v3, v3
	s_add_i32 s24, s24, -8
	s_cmp_eq_u32 s24, 0
	v_lshlrev_b32_e32 v1, 16, v1
	v_mul_f32_e32 v1, 0xbfb8aa3b, v1
	v_exp_f32_e32 v1, v1
	s_nop 0
	v_add_f32_e32 v1, 1.0, v1
	v_div_scale_f32 v6, s[26:27], v1, v1, 1.0
	v_rcp_f32_e32 v8, v6
	v_div_scale_f32 v7, vcc, 1.0, v1, 1.0
	v_fma_f32 v9, -v6, v8, 1.0
	v_fmac_f32_e32 v8, v9, v8
	v_mul_f32_e32 v9, v7, v8
	v_fma_f32 v10, -v6, v9, v7
	v_fmac_f32_e32 v9, v10, v8
	v_fma_f32 v6, -v6, v9, v7
	v_div_fmas_f32 v6, v6, v8, v9
	v_div_fixup_f32 v1, v6, v1, 1.0
	v_fma_f32 v1, v4, v1, v20
	v_sub_f32_e32 v6, 1.0, v1
	v_cmp_gt_f32_e32 vcc, s34, v1
	v_mul_f32_e32 v3, v3, v6
	s_nop 0
	v_cndmask_b32_e64 v7, 0, 32, vcc
	v_ldexp_f32 v1, v1, v7
	v_bfe_u32 v7, v3, 16, 1
	v_add3_u32 v3, v3, v7, s39
	ds_write_b16_d16_hi v2, v3 offset:14
	v_mov_b32_e32 v3, v209
	v_log_f32_e32 v1, v1
	v_cndmask_b32_e32 v6, 0, v193, vcc
	v_lshlrev_b32_e32 v3, 16, v3
	v_mul_f32_e32 v3, 0xbfb8aa3b, v3
	v_mul_f32_e32 v7, 0x3f317217, v1
	v_exp_f32_e32 v3, v3
	v_fma_f32 v7, v1, s38, -v7
	v_fmac_f32_e32 v7, 0x3377d1cf, v1
	v_fmac_f32_e32 v7, 0x3f317217, v1
	v_cmp_lt_f32_e64 vcc, |v1|, s20
	v_add_f32_e32 v3, 1.0, v3
	s_nop 0
	v_cndmask_b32_e32 v1, v1, v7, vcc
	v_sub_f32_e32 v1, v1, v6
	v_div_scale_f32 v6, s[26:27], v3, v3, 1.0
	v_rcp_f32_e32 v8, v6
	v_div_scale_f32 v7, vcc, 1.0, v3, 1.0
	v_add_f32_e32 v1, v5, v1
	v_fma_f32 v9, -v6, v8, 1.0
	v_fmac_f32_e32 v8, v9, v8
	v_mul_f32_e32 v9, v7, v8
	v_fma_f32 v10, -v6, v9, v7
	v_fmac_f32_e32 v9, v10, v8
	v_mul_f32_e32 v5, 0x3fb8aa3b, v1
	v_fma_f32 v6, -v6, v9, v7
	v_exp_f32_e32 v5, v5
	v_div_fmas_f32 v6, v6, v8, v9
	v_div_fixup_f32 v3, v6, v3, 1.0
	v_fma_f32 v3, v4, v3, v20
	v_sub_f32_e32 v6, 1.0, v3
	v_cmp_gt_f32_e32 vcc, s34, v3
	v_mul_f32_e32 v5, v5, v6
	s_nop 0
	v_cndmask_b32_e64 v7, 0, 32, vcc
	v_ldexp_f32 v3, v3, v7
	v_bfe_u32 v7, v5, 16, 1
	v_add3_u32 v5, v5, v7, s39
	ds_write_b16_d16_hi v2, v5 offset:12
	v_mov_b32_e32 v5, v210
	v_log_f32_e32 v3, v3
	v_cndmask_b32_e32 v6, 0, v193, vcc
	v_lshlrev_b32_e32 v5, 16, v5
	v_mul_f32_e32 v5, 0xbfb8aa3b, v5
	v_mul_f32_e32 v7, 0x3f317217, v3
	v_exp_f32_e32 v5, v5
	v_fma_f32 v7, v3, s38, -v7
	v_fmac_f32_e32 v7, 0x3377d1cf, v3
	v_fmac_f32_e32 v7, 0x3f317217, v3
	v_cmp_lt_f32_e64 vcc, |v3|, s20
	v_add_f32_e32 v5, 1.0, v5
	s_nop 0
	v_cndmask_b32_e32 v3, v3, v7, vcc
	v_sub_f32_e32 v3, v3, v6
	v_div_scale_f32 v6, s[26:27], v5, v5, 1.0
	v_rcp_f32_e32 v8, v6
	v_div_scale_f32 v7, vcc, 1.0, v5, 1.0
	v_add_f32_e32 v1, v1, v3
	v_fma_f32 v9, -v6, v8, 1.0
	v_fmac_f32_e32 v8, v9, v8
	v_mul_f32_e32 v9, v7, v8
	v_fma_f32 v10, -v6, v9, v7
	v_fmac_f32_e32 v9, v10, v8
	v_mul_f32_e32 v3, 0x3fb8aa3b, v1
; DEVI float b2f(bfu b) { return __uint_as_float(((unsigned)b) << 16); }
; DEVI float sigmoidf_(float x) { return 1.f / (1.f + __expf(-x)); }
; DEVI void h1_item(const Params& P, int l, int ck, int h, char* smem, int tid) {
;     ...
; #pragma unroll 8
;   for (int i = Lh - 1; i >= 0; --i) {
;     const int sr = hf * Lh + i;
;     float f = lb + (1.f - lb) * sigmoidf_(b2f(FS[sr * 136 + d]));
;     KT[d * 72 + sr] = f2b((1.f - f) * __expf(run));
;     run += __logf(f);
;   }
;   if (L == 32) {
;     for (int sr = 32 + hf * 16; sr < 48 + hf * 16; ++sr) KT[d * 72 + sr] = 0;
	v_fma_f32 v6, -v6, v9, v7
	v_exp_f32_e32 v3, v3
	v_div_fmas_f32 v6, v6, v8, v9
	v_div_fixup_f32 v5, v6, v5, 1.0
	v_fma_f32 v5, v4, v5, v20
	v_sub_f32_e32 v6, 1.0, v5
	v_cmp_gt_f32_e32 vcc, s34, v5
	v_mul_f32_e32 v3, v3, v6
	s_nop 0
	v_cndmask_b32_e64 v7, 0, 32, vcc
	v_ldexp_f32 v5, v5, v7
	v_bfe_u32 v7, v3, 16, 1
	v_add3_u32 v3, v3, v7, s39
	ds_write_b16_d16_hi v2, v3 offset:10
	v_mov_b32_e32 v3, v211
	v_log_f32_e32 v5, v5
	v_cndmask_b32_e32 v6, 0, v193, vcc
	v_lshlrev_b32_e32 v3, 16, v3
	v_mul_f32_e32 v3, 0xbfb8aa3b, v3
	v_mul_f32_e32 v7, 0x3f317217, v5
	v_exp_f32_e32 v3, v3
	v_fma_f32 v7, v5, s38, -v7
	v_fmac_f32_e32 v7, 0x3377d1cf, v5
	v_fmac_f32_e32 v7, 0x3f317217, v5
	v_cmp_lt_f32_e64 vcc, |v5|, s20
	v_add_f32_e32 v3, 1.0, v3
	s_nop 0
	v_cndmask_b32_e32 v5, v5, v7, vcc
	v_sub_f32_e32 v5, v5, v6
	v_div_scale_f32 v6, s[26:27], v3, v3, 1.0
	v_rcp_f32_e32 v8, v6
	v_div_scale_f32 v7, vcc, 1.0, v3, 1.0
	v_add_f32_e32 v1, v1, v5
	v_fma_f32 v9, -v6, v8, 1.0
	v_fmac_f32_e32 v8, v9, v8
	v_mul_f32_e32 v9, v7, v8
	v_fma_f32 v10, -v6, v9, v7
	v_fmac_f32_e32 v9, v10, v8
	v_mul_f32_e32 v5, 0x3fb8aa3b, v1
	v_fma_f32 v6, -v6, v9, v7
	v_exp_f32_e32 v5, v5
	v_div_fmas_f32 v6, v6, v8, v9
	v_div_fixup_f32 v3, v6, v3, 1.0
	v_fma_f32 v3, v4, v3, v20
	v_sub_f32_e32 v6, 1.0, v3
	v_cmp_gt_f32_e32 vcc, s34, v3
	v_mul_f32_e32 v5, v5, v6
	s_nop 0
	v_cndmask_b32_e64 v7, 0, 32, vcc
	v_ldexp_f32 v3, v3, v7
	v_bfe_u32 v7, v5, 16, 1
	v_add3_u32 v5, v5, v7, s39
	ds_write_b16_d16_hi v2, v5 offset:8
	v_mov_b32_e32 v5, v212
	v_log_f32_e32 v3, v3
	v_cndmask_b32_e32 v6, 0, v193, vcc
	v_lshlrev_b32_e32 v5, 16, v5
	v_mul_f32_e32 v5, 0xbfb8aa3b, v5
	v_mul_f32_e32 v7, 0x3f317217, v3
	v_exp_f32_e32 v5, v5
	v_fma_f32 v7, v3, s38, -v7
	v_fmac_f32_e32 v7, 0x3377d1cf, v3
	v_fmac_f32_e32 v7, 0x3f317217, v3
	v_cmp_lt_f32_e64 vcc, |v3|, s20
	v_add_f32_e32 v5, 1.0, v5
	s_nop 0
	v_cndmask_b32_e32 v3, v3, v7, vcc
	v_sub_f32_e32 v3, v3, v6
	v_div_scale_f32 v6, s[26:27], v5, v5, 1.0
	v_rcp_f32_e32 v8, v6
	v_div_scale_f32 v7, vcc, 1.0, v5, 1.0
	v_add_f32_e32 v1, v1, v3
	v_fma_f32 v9, -v6, v8, 1.0
	v_fmac_f32_e32 v8, v9, v8
	v_mul_f32_e32 v9, v7, v8
	v_fma_f32 v10, -v6, v9, v7
	v_fmac_f32_e32 v9, v10, v8
	v_mul_f32_e32 v3, 0x3fb8aa3b, v1
	v_fma_f32 v6, -v6, v9, v7
	v_exp_f32_e32 v3, v3
	v_div_fmas_f32 v6, v6, v8, v9
	v_div_fixup_f32 v5, v6, v5, 1.0
	v_fma_f32 v5, v4, v5, v20
	v_sub_f32_e32 v6, 1.0, v5
	v_cmp_gt_f32_e32 vcc, s34, v5
	v_mul_f32_e32 v3, v3, v6
	s_nop 0
	v_cndmask_b32_e64 v7, 0, 32, vcc
	v_ldexp_f32 v5, v5, v7
	v_bfe_u32 v7, v3, 16, 1
	v_add3_u32 v3, v3, v7, s39
	ds_write_b16_d16_hi v2, v3 offset:6
	v_mov_b32_e32 v3, v213
	v_log_f32_e32 v5, v5
	v_cndmask_b32_e32 v6, 0, v193, vcc
	v_lshlrev_b32_e32 v3, 16, v3
	v_mul_f32_e32 v3, 0xbfb8aa3b, v3
	v_mul_f32_e32 v7, 0x3f317217, v5
	v_exp_f32_e32 v3, v3
	v_fma_f32 v7, v5, s38, -v7
	v_fmac_f32_e32 v7, 0x3377d1cf, v5
	v_fmac_f32_e32 v7, 0x3f317217, v5
	v_cmp_lt_f32_e64 vcc, |v5|, s20
	v_add_f32_e32 v3, 1.0, v3
	s_nop 0
	v_cndmask_b32_e32 v5, v5, v7, vcc
	v_sub_f32_e32 v5, v5, v6
	v_div_scale_f32 v6, s[26:27], v3, v3, 1.0
	v_rcp_f32_e32 v8, v6
	v_div_scale_f32 v7, vcc, 1.0, v3, 1.0
	v_add_f32_e32 v1, v1, v5
	v_fma_f32 v9, -v6, v8, 1.0
	v_fmac_f32_e32 v8, v9, v8
	v_mul_f32_e32 v9, v7, v8
	v_fma_f32 v10, -v6, v9, v7
	v_fmac_f32_e32 v9, v10, v8
	v_mul_f32_e32 v5, 0x3fb8aa3b, v1
	v_fma_f32 v6, -v6, v9, v7
	v_exp_f32_e32 v5, v5
	v_div_fmas_f32 v6, v6, v8, v9
	v_div_fixup_f32 v3, v6, v3, 1.0
	v_fma_f32 v3, v4, v3, v20
	v_sub_f32_e32 v6, 1.0, v3
	v_cmp_gt_f32_e32 vcc, s34, v3
	v_mul_f32_e32 v5, v5, v6
	s_nop 0
	v_cndmask_b32_e64 v7, 0, 32, vcc
	v_ldexp_f32 v3, v3, v7
	v_bfe_u32 v7, v5, 16, 1
	v_add3_u32 v5, v5, v7, s39
	ds_write_b16_d16_hi v2, v5 offset:4
	v_mov_b32_e32 v5, v214
	v_log_f32_e32 v3, v3
	v_cndmask_b32_e32 v6, 0, v193, vcc
	v_lshlrev_b32_e32 v5, 16, v5
	v_mul_f32_e32 v5, 0xbfb8aa3b, v5
	v_mul_f32_e32 v7, 0x3f317217, v3
	v_exp_f32_e32 v5, v5
	v_fma_f32 v7, v3, s38, -v7
	v_fmac_f32_e32 v7, 0x3377d1cf, v3
	v_fmac_f32_e32 v7, 0x3f317217, v3
	v_cmp_lt_f32_e64 vcc, |v3|, s20
	v_add_f32_e32 v5, 1.0, v5
	s_nop 0
	v_cndmask_b32_e32 v3, v3, v7, vcc
	v_sub_f32_e32 v3, v3, v6
	v_div_scale_f32 v6, s[26:27], v5, v5, 1.0
	v_rcp_f32_e32 v8, v6
	v_div_scale_f32 v7, vcc, 1.0, v5, 1.0
	v_add_f32_e32 v1, v1, v3
	v_fma_f32 v9, -v6, v8, 1.0
	v_fmac_f32_e32 v8, v9, v8
	v_mul_f32_e32 v9, v7, v8
	v_fma_f32 v10, -v6, v9, v7
	v_fmac_f32_e32 v9, v10, v8
	v_mul_f32_e32 v3, 0x3fb8aa3b, v1
	v_fma_f32 v6, -v6, v9, v7
	v_exp_f32_e32 v3, v3
	v_div_fmas_f32 v6, v6, v8, v9
	v_div_fixup_f32 v5, v6, v5, 1.0
	v_fma_f32 v5, v4, v5, v20
	v_sub_f32_e32 v6, 1.0, v5
	v_cmp_gt_f32_e32 vcc, s34, v5
	v_mul_f32_e32 v3, v3, v6
	s_nop 0
	v_cndmask_b32_e64 v7, 0, 32, vcc
	v_ldexp_f32 v5, v5, v7
	v_bfe_u32 v7, v3, 16, 1
	v_add3_u32 v3, v3, v7, s39
	ds_write_b16_d16_hi v2, v3 offset:2
	v_mov_b32_e32 v3, v215
	v_log_f32_e32 v5, v5
	v_cndmask_b32_e32 v6, 0, v193, vcc
	v_add_u32_e32 v0, 0xfffff780, v0
	v_lshlrev_b32_e32 v3, 16, v3
	v_mul_f32_e32 v3, 0xbfb8aa3b, v3
	v_mul_f32_e32 v7, 0x3f317217, v5
	v_exp_f32_e32 v3, v3
	v_fma_f32 v7, v5, s38, -v7
	v_fmac_f32_e32 v7, 0x3377d1cf, v5
	v_fmac_f32_e32 v7, 0x3f317217, v5
	v_cmp_lt_f32_e64 vcc, |v5|, s20
	v_add_f32_e32 v3, 1.0, v3
	s_nop 0
	v_cndmask_b32_e32 v5, v5, v7, vcc
	v_sub_f32_e32 v5, v5, v6
	v_div_scale_f32 v6, s[26:27], v3, v3, 1.0
	v_rcp_f32_e32 v8, v6
	v_div_scale_f32 v7, vcc, 1.0, v3, 1.0
	v_add_f32_e32 v1, v1, v5
	v_fma_f32 v9, -v6, v8, 1.0
	v_fmac_f32_e32 v8, v9, v8
	v_mul_f32_e32 v9, v7, v8
	v_fma_f32 v10, -v6, v9, v7
	v_fmac_f32_e32 v9, v10, v8
	v_fma_f32 v6, -v6, v9, v7
	v_div_fmas_f32 v6, v6, v8, v9
	v_div_fixup_f32 v3, v6, v3, 1.0
	v_mul_f32_e32 v5, 0x3fb8aa3b, v1
	v_fma_f32 v3, v4, v3, v20
	v_exp_f32_e32 v5, v5
	v_cmp_gt_f32_e32 vcc, s34, v3
	v_sub_f32_e32 v6, 1.0, v3
	v_mul_f32_e32 v5, v5, v6
	v_cndmask_b32_e64 v7, 0, 32, vcc
	v_ldexp_f32 v3, v3, v7
	v_log_f32_e32 v3, v3
	v_bfe_u32 v7, v5, 16, 1
	v_add3_u32 v5, v5, v7, s39
	ds_write_b16_d16_hi v2, v5
	v_mul_f32_e32 v5, 0x3f317217, v3
	v_fma_f32 v5, v3, s38, -v5
	v_fmac_f32_e32 v5, 0x3377d1cf, v3
	v_cndmask_b32_e32 v6, 0, v193, vcc
	v_fmac_f32_e32 v5, 0x3f317217, v3
	v_cmp_lt_f32_e64 vcc, |v3|, s20
	v_add_u32_e32 v2, -16, v2
	s_nop 0
	v_cndmask_b32_e32 v3, v3, v5, vcc
	v_sub_f32_e32 v3, v3, v6
	v_add_f32_e32 v5, v1, v3
	s_cbranch_scc0 .LBB0_401
	s_and_b64 vcc, exec, s[46:47]
	s_cbranch_vccz .LBB0_404
	s_mov_b32 s24, s25
	s_mov_b32 s26, s25
	s_mov_b32 s27, s25
	v_mov_b64_e32 v[0:1], s[24:25]
	v_mov_b64_e32 v[2:3], s[26:27]
	ds_write_b128 v166, v[0:3] offset:18496
	ds_write_b128 v166, v[0:3] offset:18512

; DEVI float b2f(bfu b) { return __uint_as_float(((unsigned)b) << 16); }
; DEVI float sigmoidf_(float x) { return 1.f / (1.f + __expf(-x)); }
; DEVI float siluf_(float x) { return x / (1.f + __expf(-x)); }
; DEVI void h3_item(const Params& P, int l, int ck, int h, char* smem, int tid) {
;     ...
;     float rel = 0.f;
; #pragma unroll 8
;     for (int t = Lh; t < L; ++t) {
;       float f = lb + (1.f - lb) * sigmoidf_(b2f(KT[t * 136 + d]));
;       float q = siluf_(b2f(QT[t * 136 + d]));
;       rel += __logf(f);
;       QT[t * 136 + d] = f2b(q * __expf(rel));
;       KT[t * 136 + d] = f2b((1.f - f) * __expf(fminf(-rel, 80.f)));
;     }
.LBB0_553:
	ds_read_u16 v228, v1 offset:17408
	ds_read_u16 v229, v1
	ds_read_u16 v230, v1 offset:17680
	ds_read_u16 v231, v1 offset:272
	ds_read_u16 v232, v1 offset:17952
	ds_read_u16 v233, v1 offset:544
	ds_read_u16 v234, v1 offset:18224
	ds_read_u16 v235, v1 offset:816
	ds_read_u16 v236, v1 offset:18496
	ds_read_u16 v237, v1 offset:1088
	ds_read_u16 v238, v1 offset:18768
	ds_read_u16 v239, v1 offset:1360
	ds_read_u16 v240, v1 offset:19040
	ds_read_u16 v241, v1 offset:1632
	ds_read_u16 v242, v1 offset:19312
	ds_read_u16 v243, v1 offset:1904
	s_waitcnt lgkmcnt(0)
	v_mov_b32_e32 v3, v228
	s_add_i32 s55, s55, 8
	s_cmp_lt_u32 s55, s51
	v_lshlrev_b32_e32 v3, 16, v3
	v_mul_f32_e32 v3, 0xbfb8aa3b, v3
	v_exp_f32_e32 v3, v3
	s_nop 0
	v_add_f32_e32 v3, 1.0, v3
	v_div_scale_f32 v4, s[58:59], v3, v3, 1.0
	v_rcp_f32_e32 v5, v4
	s_nop 0
	v_fma_f32 v6, -v4, v5, 1.0
	v_fmac_f32_e32 v5, v6, v5
	v_div_scale_f32 v6, vcc, 1.0, v3, 1.0
	v_mul_f32_e32 v7, v6, v5
	v_fma_f32 v8, -v4, v7, v6
	v_fmac_f32_e32 v7, v8, v5
	v_fma_f32 v4, -v4, v7, v6
	v_div_fmas_f32 v4, v4, v5, v7
	v_div_fixup_f32 v3, v4, v3, 1.0
	v_mov_b32_e32 v4, v229
	v_fma_f32 v3, v0, v3, v58
	v_lshlrev_b32_e32 v4, 16, v4
	v_mul_f32_e32 v5, 0xbfb8aa3b, v4
	v_exp_f32_e32 v5, v5
	s_nop 0
	v_add_f32_e32 v5, 1.0, v5
	v_div_scale_f32 v6, s[58:59], v5, v5, v4
	v_rcp_f32_e32 v7, v6
	s_nop 0
	v_fma_f32 v8, -v6, v7, 1.0
	v_fmac_f32_e32 v7, v8, v7
	v_div_scale_f32 v8, vcc, v4, v5, v4
	v_mul_f32_e32 v9, v8, v7
	v_fma_f32 v10, -v6, v9, v8
	v_fmac_f32_e32 v9, v10, v7
	v_fma_f32 v6, -v6, v9, v8
	v_div_fmas_f32 v6, v6, v7, v9
	v_cmp_gt_f32_e32 vcc, s34, v3
	v_div_fixup_f32 v4, v6, v5, v4
	s_nop 0
	v_cndmask_b32_e64 v5, 0, 32, vcc
	v_ldexp_f32 v5, v3, v5
	v_log_f32_e32 v5, v5
	v_sub_f32_e32 v3, 1.0, v3
	v_mul_f32_e32 v6, 0x3f317217, v5
	v_fma_f32 v6, v5, s38, -v6
	v_fmac_f32_e32 v6, 0x3377d1cf, v5
	v_fmac_f32_e32 v6, 0x3f317217, v5
	v_cmp_lt_f32_e64 s[82:83], |v5|, s20
	s_nop 1
	v_cndmask_b32_e64 v5, v5, v6, s[82:83]
	v_cndmask_b32_e32 v6, 0, v193, vcc
	v_sub_f32_e32 v5, v5, v6
	v_add_f32_e32 v2, v2, v5
	v_mul_f32_e32 v5, 0x3fb8aa3b, v2
	v_exp_f32_e32 v5, v5
	s_nop 0
	v_mul_f32_e32 v4, v4, v5
	v_bfe_u32 v5, v4, 16, 1
	v_add3_u32 v4, v4, v5, s39
	ds_write_b16_d16_hi v1, v4
	v_min_f32_e64 v4, -v2, s4
	v_mul_f32_e32 v4, 0x3fb8aa3b, v4
	v_exp_f32_e32 v4, v4
	s_nop 0
	v_mul_f32_e32 v3, v3, v4
	v_bfe_u32 v4, v3, 16, 1
	v_add3_u32 v3, v3, v4, s39
	ds_write_b16_d16_hi v1, v3 offset:17408
	v_mov_b32_e32 v3, v230
	v_lshlrev_b32_e32 v3, 16, v3
	v_mul_f32_e32 v3, 0xbfb8aa3b, v3
	v_exp_f32_e32 v3, v3
	s_nop 0
	v_add_f32_e32 v3, 1.0, v3
	v_div_scale_f32 v4, s[58:59], v3, v3, 1.0
	v_rcp_f32_e32 v5, v4
	s_nop 0
	v_fma_f32 v6, -v4, v5, 1.0
	v_fmac_f32_e32 v5, v6, v5
	v_div_scale_f32 v6, vcc, 1.0, v3, 1.0
	v_mul_f32_e32 v7, v6, v5
	v_fma_f32 v8, -v4, v7, v6
	v_fmac_f32_e32 v7, v8, v5
	v_fma_f32 v4, -v4, v7, v6
	v_div_fmas_f32 v4, v4, v5, v7
	v_div_fixup_f32 v3, v4, v3, 1.0
	v_mov_b32_e32 v4, v231
	v_fma_f32 v3, v0, v3, v58
	v_lshlrev_b32_e32 v4, 16, v4
	v_mul_f32_e32 v5, 0xbfb8aa3b, v4
	v_exp_f32_e32 v5, v5
	s_nop 0
	v_add_f32_e32 v5, 1.0, v5
	v_div_scale_f32 v6, s[58:59], v5, v5, v4
	v_rcp_f32_e32 v7, v6
	s_nop 0
	v_fma_f32 v8, -v6, v7, 1.0
	v_fmac_f32_e32 v7, v8, v7
	v_div_scale_f32 v8, vcc, v4, v5, v4
	v_mul_f32_e32 v9, v8, v7
	v_fma_f32 v10, -v6, v9, v8
	v_fmac_f32_e32 v9, v10, v7
	v_fma_f32 v6, -v6, v9, v8
	v_div_fmas_f32 v6, v6, v7, v9
	v_cmp_gt_f32_e32 vcc, s34, v3
	v_div_fixup_f32 v4, v6, v5, v4
	s_nop 0
	v_cndmask_b32_e64 v5, 0, 32, vcc
	v_ldexp_f32 v5, v3, v5
	v_log_f32_e32 v5, v5
	v_sub_f32_e32 v3, 1.0, v3
	v_mul_f32_e32 v6, 0x3f317217, v5
	v_fma_f32 v6, v5, s38, -v6
	v_fmac_f32_e32 v6, 0x3377d1cf, v5
	v_fmac_f32_e32 v6, 0x3f317217, v5
	v_cmp_lt_f32_e64 s[82:83], |v5|, s20
	s_nop 1
	v_cndmask_b32_e64 v5, v5, v6, s[82:83]
	v_cndmask_b32_e32 v6, 0, v193, vcc
	v_sub_f32_e32 v5, v5, v6
	v_add_f32_e32 v2, v2, v5
	v_mul_f32_e32 v5, 0x3fb8aa3b, v2
	v_exp_f32_e32 v5, v5
	s_nop 0
	v_mul_f32_e32 v4, v4, v5
	v_bfe_u32 v5, v4, 16, 1
	v_add3_u32 v4, v4, v5, s39
	ds_write_b16_d16_hi v1, v4 offset:272
	v_min_f32_e64 v4, -v2, s4
	v_mul_f32_e32 v4, 0x3fb8aa3b, v4
	v_exp_f32_e32 v4, v4
	s_nop 0
	v_mul_f32_e32 v3, v3, v4
	v_bfe_u32 v4, v3, 16, 1
	v_add3_u32 v3, v3, v4, s39
	ds_write_b16_d16_hi v1, v3 offset:17680
	v_mov_b32_e32 v3, v232
	v_lshlrev_b32_e32 v3, 16, v3
	v_mul_f32_e32 v3, 0xbfb8aa3b, v3
	v_exp_f32_e32 v3, v3
	s_nop 0
	v_add_f32_e32 v3, 1.0, v3
	v_div_scale_f32 v4, s[58:59], v3, v3, 1.0
	v_rcp_f32_e32 v5, v4
	s_nop 0
	v_fma_f32 v6, -v4, v5, 1.0
	v_fmac_f32_e32 v5, v6, v5
	v_div_scale_f32 v6, vcc, 1.0, v3, 1.0
	v_mul_f32_e32 v7, v6, v5
	v_fma_f32 v8, -v4, v7, v6
	v_fmac_f32_e32 v7, v8, v5
	v_fma_f32 v4, -v4, v7, v6
	v_div_fmas_f32 v4, v4, v5, v7
	v_div_fixup_f32 v3, v4, v3, 1.0
	v_mov_b32_e32 v4, v233
	v_fma_f32 v3, v0, v3, v58
	v_lshlrev_b32_e32 v4, 16, v4
	v_mul_f32_e32 v5, 0xbfb8aa3b, v4
	v_exp_f32_e32 v5, v5
	s_nop 0
	v_add_f32_e32 v5, 1.0, v5
	v_div_scale_f32 v6, s[58:59], v5, v5, v4
	v_rcp_f32_e32 v7, v6
	s_nop 0
	v_fma_f32 v8, -v6, v7, 1.0
	v_fmac_f32_e32 v7, v8, v7
	v_div_scale_f32 v8, vcc, v4, v5, v4
	v_mul_f32_e32 v9, v8, v7
	v_fma_f32 v10, -v6, v9, v8
	v_fmac_f32_e32 v9, v10, v7
	v_fma_f32 v6, -v6, v9, v8
	v_div_fmas_f32 v6, v6, v7, v9
	v_cmp_gt_f32_e32 vcc, s34, v3
	v_div_fixup_f32 v4, v6, v5, v4
	s_nop 0
	v_cndmask_b32_e64 v5, 0, 32, vcc
	v_ldexp_f32 v5, v3, v5
	v_log_f32_e32 v5, v5
	v_sub_f32_e32 v3, 1.0, v3
	v_mul_f32_e32 v6, 0x3f317217, v5
	v_fma_f32 v6, v5, s38, -v6
	v_fmac_f32_e32 v6, 0x3377d1cf, v5
	v_fmac_f32_e32 v6, 0x3f317217, v5
	v_cmp_lt_f32_e64 s[82:83], |v5|, s20
	s_nop 1
	v_cndmask_b32_e64 v5, v5, v6, s[82:83]
; DEVI float b2f(bfu b) { return __uint_as_float(((unsigned)b) << 16); }
; DEVI float sigmoidf_(float x) { return 1.f / (1.f + __expf(-x)); }
; DEVI float siluf_(float x) { return x / (1.f + __expf(-x)); }
; DEVI void h3_item(const Params& P, int l, int ck, int h, char* smem, int tid) {
;     ...
;     for (int t = Lh; t < L; ++t) {
;       float f = lb + (1.f - lb) * sigmoidf_(b2f(KT[t * 136 + d]));
;       float q = siluf_(b2f(QT[t * 136 + d]));
;       rel += __logf(f);
;       QT[t * 136 + d] = f2b(q * __expf(rel));
;       KT[t * 136 + d] = f2b((1.f - f) * __expf(fminf(-rel, 80.f)));
;     }
	v_cndmask_b32_e32 v6, 0, v193, vcc
	v_sub_f32_e32 v5, v5, v6
	v_add_f32_e32 v2, v2, v5
	v_mul_f32_e32 v5, 0x3fb8aa3b, v2
	v_exp_f32_e32 v5, v5
	s_nop 0
	v_mul_f32_e32 v4, v4, v5
	v_bfe_u32 v5, v4, 16, 1
	v_add3_u32 v4, v4, v5, s39
	ds_write_b16_d16_hi v1, v4 offset:544
	v_min_f32_e64 v4, -v2, s4
	v_mul_f32_e32 v4, 0x3fb8aa3b, v4
	v_exp_f32_e32 v4, v4
	s_nop 0
	v_mul_f32_e32 v3, v3, v4
	v_bfe_u32 v4, v3, 16, 1
	v_add3_u32 v3, v3, v4, s39
	ds_write_b16_d16_hi v1, v3 offset:17952
	v_mov_b32_e32 v3, v234
	v_lshlrev_b32_e32 v3, 16, v3
	v_mul_f32_e32 v3, 0xbfb8aa3b, v3
	v_exp_f32_e32 v3, v3
	s_nop 0
	v_add_f32_e32 v3, 1.0, v3
	v_div_scale_f32 v4, s[58:59], v3, v3, 1.0
	v_rcp_f32_e32 v5, v4
	s_nop 0
	v_fma_f32 v6, -v4, v5, 1.0
	v_fmac_f32_e32 v5, v6, v5
	v_div_scale_f32 v6, vcc, 1.0, v3, 1.0
	v_mul_f32_e32 v7, v6, v5
	v_fma_f32 v8, -v4, v7, v6
	v_fmac_f32_e32 v7, v8, v5
	v_fma_f32 v4, -v4, v7, v6
	v_div_fmas_f32 v4, v4, v5, v7
	v_div_fixup_f32 v3, v4, v3, 1.0
	v_mov_b32_e32 v4, v235
	v_fma_f32 v3, v0, v3, v58
	v_lshlrev_b32_e32 v4, 16, v4
	v_mul_f32_e32 v5, 0xbfb8aa3b, v4
	v_exp_f32_e32 v5, v5
	s_nop 0
	v_add_f32_e32 v5, 1.0, v5
	v_div_scale_f32 v6, s[58:59], v5, v5, v4
	v_rcp_f32_e32 v7, v6
	s_nop 0
	v_fma_f32 v8, -v6, v7, 1.0
	v_fmac_f32_e32 v7, v8, v7
	v_div_scale_f32 v8, vcc, v4, v5, v4
	v_mul_f32_e32 v9, v8, v7
	v_fma_f32 v10, -v6, v9, v8
	v_fmac_f32_e32 v9, v10, v7
	v_fma_f32 v6, -v6, v9, v8
	v_div_fmas_f32 v6, v6, v7, v9
	v_cmp_gt_f32_e32 vcc, s34, v3
	v_div_fixup_f32 v4, v6, v5, v4
	s_nop 0
	v_cndmask_b32_e64 v5, 0, 32, vcc
	v_ldexp_f32 v5, v3, v5
	v_log_f32_e32 v5, v5
	v_sub_f32_e32 v3, 1.0, v3
	v_mul_f32_e32 v6, 0x3f317217, v5
	v_fma_f32 v6, v5, s38, -v6
	v_fmac_f32_e32 v6, 0x3377d1cf, v5
	v_fmac_f32_e32 v6, 0x3f317217, v5
	v_cmp_lt_f32_e64 s[82:83], |v5|, s20
	s_nop 1
	v_cndmask_b32_e64 v5, v5, v6, s[82:83]
	v_cndmask_b32_e32 v6, 0, v193, vcc
	v_sub_f32_e32 v5, v5, v6
	v_add_f32_e32 v2, v2, v5
	v_mul_f32_e32 v5, 0x3fb8aa3b, v2
	v_exp_f32_e32 v5, v5
	s_nop 0
	v_mul_f32_e32 v4, v4, v5
	v_bfe_u32 v5, v4, 16, 1
	v_add3_u32 v4, v4, v5, s39
	ds_write_b16_d16_hi v1, v4 offset:816
	v_min_f32_e64 v4, -v2, s4
	v_mul_f32_e32 v4, 0x3fb8aa3b, v4
	v_exp_f32_e32 v4, v4
	s_nop 0
	v_mul_f32_e32 v3, v3, v4
	v_bfe_u32 v4, v3, 16, 1
	v_add3_u32 v3, v3, v4, s39
	ds_write_b16_d16_hi v1, v3 offset:18224
	v_mov_b32_e32 v3, v236
	v_lshlrev_b32_e32 v3, 16, v3
	v_mul_f32_e32 v3, 0xbfb8aa3b, v3
	v_exp_f32_e32 v3, v3
	s_nop 0
	v_add_f32_e32 v3, 1.0, v3
	v_div_scale_f32 v4, s[58:59], v3, v3, 1.0
	v_rcp_f32_e32 v5, v4
	s_nop 0
	v_fma_f32 v6, -v4, v5, 1.0
	v_fmac_f32_e32 v5, v6, v5
	v_div_scale_f32 v6, vcc, 1.0, v3, 1.0
	v_mul_f32_e32 v7, v6, v5
	v_fma_f32 v8, -v4, v7, v6
	v_fmac_f32_e32 v7, v8, v5
	v_fma_f32 v4, -v4, v7, v6
	v_div_fmas_f32 v4, v4, v5, v7
	v_div_fixup_f32 v3, v4, v3, 1.0
	v_mov_b32_e32 v4, v237
	v_fma_f32 v3, v0, v3, v58
	v_lshlrev_b32_e32 v4, 16, v4
	v_mul_f32_e32 v5, 0xbfb8aa3b, v4
	v_exp_f32_e32 v5, v5
	s_nop 0
	v_add_f32_e32 v5, 1.0, v5
	v_div_scale_f32 v6, s[58:59], v5, v5, v4
	v_rcp_f32_e32 v7, v6
	s_nop 0
	v_fma_f32 v8, -v6, v7, 1.0
	v_fmac_f32_e32 v7, v8, v7
	v_div_scale_f32 v8, vcc, v4, v5, v4
	v_mul_f32_e32 v9, v8, v7
	v_fma_f32 v10, -v6, v9, v8
	v_fmac_f32_e32 v9, v10, v7
	v_fma_f32 v6, -v6, v9, v8
	v_div_fmas_f32 v6, v6, v7, v9
	v_cmp_gt_f32_e32 vcc, s34, v3
	v_div_fixup_f32 v4, v6, v5, v4
	s_nop 0
	v_cndmask_b32_e64 v5, 0, 32, vcc
	v_ldexp_f32 v5, v3, v5
	v_log_f32_e32 v5, v5
	v_sub_f32_e32 v3, 1.0, v3
	v_mul_f32_e32 v6, 0x3f317217, v5
	v_fma_f32 v6, v5, s38, -v6
	v_fmac_f32_e32 v6, 0x3377d1cf, v5
	v_fmac_f32_e32 v6, 0x3f317217, v5
	v_cmp_lt_f32_e64 s[82:83], |v5|, s20
	s_nop 1
	v_cndmask_b32_e64 v5, v5, v6, s[82:83]
	v_cndmask_b32_e32 v6, 0, v193, vcc
	v_sub_f32_e32 v5, v5, v6
	v_add_f32_e32 v2, v2, v5
	v_mul_f32_e32 v5, 0x3fb8aa3b, v2
	v_exp_f32_e32 v5, v5
	s_nop 0
	v_mul_f32_e32 v4, v4, v5
	v_bfe_u32 v5, v4, 16, 1
	v_add3_u32 v4, v4, v5, s39
	ds_write_b16_d16_hi v1, v4 offset:1088
	v_min_f32_e64 v4, -v2, s4
	v_mul_f32_e32 v4, 0x3fb8aa3b, v4
	v_exp_f32_e32 v4, v4
	s_nop 0
	v_mul_f32_e32 v3, v3, v4
	v_bfe_u32 v4, v3, 16, 1
	v_add3_u32 v3, v3, v4, s39
	ds_write_b16_d16_hi v1, v3 offset:18496
	v_mov_b32_e32 v3, v238
	v_lshlrev_b32_e32 v3, 16, v3
	v_mul_f32_e32 v3, 0xbfb8aa3b, v3
	v_exp_f32_e32 v3, v3
	s_nop 0
	v_add_f32_e32 v3, 1.0, v3
	v_div_scale_f32 v4, s[58:59], v3, v3, 1.0
	v_rcp_f32_e32 v5, v4
	s_nop 0
	v_fma_f32 v6, -v4, v5, 1.0
	v_fmac_f32_e32 v5, v6, v5
	v_div_scale_f32 v6, vcc, 1.0, v3, 1.0
	v_mul_f32_e32 v7, v6, v5
	v_fma_f32 v8, -v4, v7, v6
	v_fmac_f32_e32 v7, v8, v5
	v_fma_f32 v4, -v4, v7, v6
	v_div_fmas_f32 v4, v4, v5, v7
	v_div_fixup_f32 v3, v4, v3, 1.0
	v_mov_b32_e32 v4, v239
	v_fma_f32 v3, v0, v3, v58
	v_lshlrev_b32_e32 v4, 16, v4
	v_mul_f32_e32 v5, 0xbfb8aa3b, v4
	v_exp_f32_e32 v5, v5
	s_nop 0
	v_add_f32_e32 v5, 1.0, v5
	v_div_scale_f32 v6, s[58:59], v5, v5, v4
; DEVI float b2f(bfu b) { return __uint_as_float(((unsigned)b) << 16); }
; DEVI float sigmoidf_(float x) { return 1.f / (1.f + __expf(-x)); }
; DEVI float siluf_(float x) { return x / (1.f + __expf(-x)); }
; DEVI void h3_item(const Params& P, int l, int ck, int h, char* smem, int tid) {
;     ...
;     for (int t = Lh; t < L; ++t) {
;       float f = lb + (1.f - lb) * sigmoidf_(b2f(KT[t * 136 + d]));
;       float q = siluf_(b2f(QT[t * 136 + d]));
;       rel += __logf(f);
;       QT[t * 136 + d] = f2b(q * __expf(rel));
;       KT[t * 136 + d] = f2b((1.f - f) * __expf(fminf(-rel, 80.f)));
;     }
	v_rcp_f32_e32 v7, v6
	s_nop 0
	v_fma_f32 v8, -v6, v7, 1.0
	v_fmac_f32_e32 v7, v8, v7
	v_div_scale_f32 v8, vcc, v4, v5, v4
	v_mul_f32_e32 v9, v8, v7
	v_fma_f32 v10, -v6, v9, v8
	v_fmac_f32_e32 v9, v10, v7
	v_fma_f32 v6, -v6, v9, v8
	v_div_fmas_f32 v6, v6, v7, v9
	v_cmp_gt_f32_e32 vcc, s34, v3
	v_div_fixup_f32 v4, v6, v5, v4
	s_nop 0
	v_cndmask_b32_e64 v5, 0, 32, vcc
	v_ldexp_f32 v5, v3, v5
	v_log_f32_e32 v5, v5
	v_sub_f32_e32 v3, 1.0, v3
	v_mul_f32_e32 v6, 0x3f317217, v5
	v_fma_f32 v6, v5, s38, -v6
	v_fmac_f32_e32 v6, 0x3377d1cf, v5
	v_fmac_f32_e32 v6, 0x3f317217, v5
	v_cmp_lt_f32_e64 s[82:83], |v5|, s20
	s_nop 1
	v_cndmask_b32_e64 v5, v5, v6, s[82:83]
	v_cndmask_b32_e32 v6, 0, v193, vcc
	v_sub_f32_e32 v5, v5, v6
	v_add_f32_e32 v2, v2, v5
	v_mul_f32_e32 v5, 0x3fb8aa3b, v2
	v_exp_f32_e32 v5, v5
	s_nop 0
	v_mul_f32_e32 v4, v4, v5
	v_bfe_u32 v5, v4, 16, 1
	v_add3_u32 v4, v4, v5, s39
	ds_write_b16_d16_hi v1, v4 offset:1360
	v_min_f32_e64 v4, -v2, s4
	v_mul_f32_e32 v4, 0x3fb8aa3b, v4
	v_exp_f32_e32 v4, v4
	s_nop 0
	v_mul_f32_e32 v3, v3, v4
	v_bfe_u32 v4, v3, 16, 1
	v_add3_u32 v3, v3, v4, s39
	ds_write_b16_d16_hi v1, v3 offset:18768
	v_mov_b32_e32 v3, v240
	v_lshlrev_b32_e32 v3, 16, v3
	v_mul_f32_e32 v3, 0xbfb8aa3b, v3
	v_exp_f32_e32 v3, v3
	s_nop 0
	v_add_f32_e32 v3, 1.0, v3
	v_div_scale_f32 v4, s[58:59], v3, v3, 1.0
	v_rcp_f32_e32 v5, v4
	s_nop 0
	v_fma_f32 v6, -v4, v5, 1.0
	v_fmac_f32_e32 v5, v6, v5
	v_div_scale_f32 v6, vcc, 1.0, v3, 1.0
	v_mul_f32_e32 v7, v6, v5
	v_fma_f32 v8, -v4, v7, v6
	v_fmac_f32_e32 v7, v8, v5
	v_fma_f32 v4, -v4, v7, v6
	v_div_fmas_f32 v4, v4, v5, v7
	v_div_fixup_f32 v3, v4, v3, 1.0
	v_mov_b32_e32 v4, v241
	v_fma_f32 v3, v0, v3, v58
	v_lshlrev_b32_e32 v4, 16, v4
	v_mul_f32_e32 v5, 0xbfb8aa3b, v4
	v_exp_f32_e32 v5, v5
	s_nop 0
	v_add_f32_e32 v5, 1.0, v5
	v_div_scale_f32 v6, s[58:59], v5, v5, v4
	v_rcp_f32_e32 v7, v6
	s_nop 0
	v_fma_f32 v8, -v6, v7, 1.0
	v_fmac_f32_e32 v7, v8, v7
	v_div_scale_f32 v8, vcc, v4, v5, v4
	v_mul_f32_e32 v9, v8, v7
	v_fma_f32 v10, -v6, v9, v8
	v_fmac_f32_e32 v9, v10, v7
	v_fma_f32 v6, -v6, v9, v8
	v_div_fmas_f32 v6, v6, v7, v9
	v_cmp_gt_f32_e32 vcc, s34, v3
	v_div_fixup_f32 v4, v6, v5, v4
	s_nop 0
	v_cndmask_b32_e64 v5, 0, 32, vcc
	v_ldexp_f32 v5, v3, v5
	v_log_f32_e32 v5, v5
	v_sub_f32_e32 v3, 1.0, v3
	v_mul_f32_e32 v6, 0x3f317217, v5
	v_fma_f32 v6, v5, s38, -v6
	v_fmac_f32_e32 v6, 0x3377d1cf, v5
	v_fmac_f32_e32 v6, 0x3f317217, v5
	v_cmp_lt_f32_e64 s[82:83], |v5|, s20
	s_nop 1
	v_cndmask_b32_e64 v5, v5, v6, s[82:83]
	v_cndmask_b32_e32 v6, 0, v193, vcc
	v_sub_f32_e32 v5, v5, v6
	v_add_f32_e32 v2, v2, v5
	v_mul_f32_e32 v5, 0x3fb8aa3b, v2
	v_exp_f32_e32 v5, v5
	s_nop 0
	v_mul_f32_e32 v4, v4, v5
	v_bfe_u32 v5, v4, 16, 1
	v_add3_u32 v4, v4, v5, s39
	ds_write_b16_d16_hi v1, v4 offset:1632
	v_min_f32_e64 v4, -v2, s4
	v_mul_f32_e32 v4, 0x3fb8aa3b, v4
	v_exp_f32_e32 v4, v4
	s_nop 0
	v_mul_f32_e32 v3, v3, v4
	v_bfe_u32 v4, v3, 16, 1
	v_add3_u32 v3, v3, v4, s39
	ds_write_b16_d16_hi v1, v3 offset:19040
	v_mov_b32_e32 v3, v242
	v_lshlrev_b32_e32 v3, 16, v3
	v_mul_f32_e32 v3, 0xbfb8aa3b, v3
	v_exp_f32_e32 v3, v3
	s_nop 0
	v_add_f32_e32 v3, 1.0, v3
	v_div_scale_f32 v4, s[58:59], v3, v3, 1.0
	v_rcp_f32_e32 v5, v4
	s_nop 0
	v_fma_f32 v6, -v4, v5, 1.0
	v_fmac_f32_e32 v5, v6, v5
	v_div_scale_f32 v6, vcc, 1.0, v3, 1.0
	v_mul_f32_e32 v7, v6, v5
	v_fma_f32 v8, -v4, v7, v6
	v_fmac_f32_e32 v7, v8, v5
	v_fma_f32 v4, -v4, v7, v6
	v_div_fmas_f32 v4, v4, v5, v7
	v_div_fixup_f32 v3, v4, v3, 1.0
	v_mov_b32_e32 v4, v243
	v_fma_f32 v3, v0, v3, v58
	v_lshlrev_b32_e32 v4, 16, v4
	v_mul_f32_e32 v5, 0xbfb8aa3b, v4
	v_exp_f32_e32 v5, v5
	s_nop 0
	v_add_f32_e32 v5, 1.0, v5
	v_div_scale_f32 v6, s[58:59], v5, v5, v4
	v_rcp_f32_e32 v7, v6
	s_nop 0
	v_fma_f32 v8, -v6, v7, 1.0
	v_fmac_f32_e32 v7, v8, v7
	v_div_scale_f32 v8, vcc, v4, v5, v4
	v_mul_f32_e32 v9, v8, v7
	v_fma_f32 v10, -v6, v9, v8
	v_fmac_f32_e32 v9, v10, v7
	v_fma_f32 v6, -v6, v9, v8
	v_div_fmas_f32 v6, v6, v7, v9
	v_cmp_gt_f32_e32 vcc, s34, v3
	v_div_fixup_f32 v4, v6, v5, v4
	s_nop 0
	v_cndmask_b32_e64 v5, 0, 32, vcc
	v_ldexp_f32 v5, v3, v5
	v_log_f32_e32 v5, v5
	v_sub_f32_e32 v3, 1.0, v3
	v_mul_f32_e32 v6, 0x3f317217, v5
	v_fma_f32 v6, v5, s38, -v6
	v_fmac_f32_e32 v6, 0x3377d1cf, v5
	v_fmac_f32_e32 v6, 0x3f317217, v5
	v_cmp_lt_f32_e64 s[82:83], |v5|, s20
	s_nop 1
	v_cndmask_b32_e64 v5, v5, v6, s[82:83]
	v_cndmask_b32_e32 v6, 0, v193, vcc
	v_sub_f32_e32 v5, v5, v6
	v_add_f32_e32 v2, v2, v5
	v_mul_f32_e32 v5, 0x3fb8aa3b, v2
	v_exp_f32_e32 v5, v5
	s_nop 0
	v_mul_f32_e32 v4, v4, v5
	v_bfe_u32 v5, v4, 16, 1
	v_add3_u32 v4, v4, v5, s39
	ds_write_b16_d16_hi v1, v4 offset:1904
	v_min_f32_e64 v4, -v2, s4
	v_mul_f32_e32 v4, 0x3fb8aa3b, v4
	v_exp_f32_e32 v4, v4
	s_nop 0
	v_mul_f32_e32 v3, v3, v4
	v_bfe_u32 v4, v3, 16, 1
	v_add3_u32 v3, v3, v4, s39
	ds_write_b16_d16_hi v1, v3 offset:19312
	v_add_u32_e32 v1, 0x880, v1
	s_cbranch_scc1 .LBB0_553

; DEVI float b2f(bfu b) { return __uint_as_float(((unsigned)b) << 16); }
; DEVI float sigmoidf_(float x) { return 1.f / (1.f + __expf(-x)); }
; DEVI float siluf_(float x) { return x / (1.f + __expf(-x)); }
; DEVI void h3_item(const Params& P, int l, int ck, int h, char* smem, int tid) {
;     ...
;   if (hf == 0) {
;     float rel = 0.f;
; #pragma unroll 8
;     for (int t = Lh - 1; t >= 0; --t) {
;       float f = lb + (1.f - lb) * sigmoidf_(b2f(KT[t * 136 + d]));
;       float q = siluf_(b2f(QT[t * 136 + d]));
;       QT[t * 136 + d] = f2b(q * __expf(fminf(rel, 80.f)));
;       KT[t * 136 + d] = f2b((1.f - f) * __expf(-rel));
;       rel -= __logf(f);
;     }
;     bmid[d] = -rel;
.LBB0_556:
	v_add_u32_e32 v244, s55, v205
	ds_read_u16 v228, v244 offset:19312
	v_add_u32_e32 v244, s55, v205
	ds_read_u16 v229, v244 offset:1904
	v_add_u32_e32 v244, s55, v205
	ds_read_u16 v230, v244 offset:19040
	v_add_u32_e32 v244, s55, v205
	ds_read_u16 v231, v244 offset:1632
	v_add_u32_e32 v244, s55, v205
	ds_read_u16 v232, v244 offset:18768
	v_add_u32_e32 v244, s55, v205
	ds_read_u16 v233, v244 offset:1360
	v_add_u32_e32 v244, s55, v205
	ds_read_u16 v234, v244 offset:18496
	v_add_u32_e32 v244, s55, v205
	ds_read_u16 v235, v244 offset:1088
	v_add_u32_e32 v244, s55, v205
	ds_read_u16 v236, v244 offset:18224
	v_add_u32_e32 v244, s55, v205
	ds_read_u16 v237, v244 offset:816
	v_add_u32_e32 v244, s55, v205
	ds_read_u16 v238, v244 offset:17952
	v_add_u32_e32 v244, s55, v205
	ds_read_u16 v239, v244 offset:544
	v_add_u32_e32 v244, s55, v205
	ds_read_u16 v240, v244 offset:17680
	v_add_u32_e32 v244, s55, v205
	ds_read_u16 v241, v244 offset:272
	v_add_u32_e32 v244, s55, v205
	ds_read_u16 v242, v244 offset:17408
	v_add_u32_e32 v244, s55, v205
	ds_read_u16 v243, v244
	s_waitcnt lgkmcnt(0)
	v_add_u32_e32 v2, s55, v205
	v_mov_b32_e32 v3, v228
	s_addk_i32 s55, 0xf780
	s_cmp_eq_u32 s55, 0
	v_lshlrev_b32_e32 v3, 16, v3
	v_mul_f32_e32 v3, 0xbfb8aa3b, v3
	v_exp_f32_e32 v3, v3
	s_nop 0
	v_add_f32_e32 v3, 1.0, v3
	v_div_scale_f32 v4, s[56:57], v3, v3, 1.0
	v_rcp_f32_e32 v5, v4
	s_nop 0
	v_fma_f32 v6, -v4, v5, 1.0
	v_fmac_f32_e32 v5, v6, v5
	v_div_scale_f32 v6, vcc, 1.0, v3, 1.0
	v_mul_f32_e32 v7, v6, v5
	v_fma_f32 v8, -v4, v7, v6
	v_fmac_f32_e32 v7, v8, v5
	v_fma_f32 v4, -v4, v7, v6
	v_div_fmas_f32 v4, v4, v5, v7
	v_div_fixup_f32 v3, v4, v3, 1.0
	v_mov_b32_e32 v4, v229
	v_fma_f32 v3, v0, v3, v58
	v_lshlrev_b32_e32 v4, 16, v4
	v_mul_f32_e32 v5, 0xbfb8aa3b, v4
	v_exp_f32_e32 v5, v5
	s_nop 0
	v_add_f32_e32 v5, 1.0, v5
	v_div_scale_f32 v6, s[56:57], v5, v5, v4
	v_rcp_f32_e32 v7, v6
	s_nop 0
	v_fma_f32 v8, -v6, v7, 1.0
	v_fmac_f32_e32 v7, v8, v7
	v_div_scale_f32 v8, vcc, v4, v5, v4
	v_mul_f32_e32 v9, v8, v7
	v_fma_f32 v10, -v6, v9, v8
	v_fmac_f32_e32 v9, v10, v7
	v_fma_f32 v6, -v6, v9, v8
	v_div_fmas_f32 v6, v6, v7, v9
	v_div_fixup_f32 v4, v6, v5, v4
	v_max_f32_e32 v5, v1, v1
	v_min_f32_e32 v5, 0x42a00000, v5
	v_mul_f32_e32 v5, 0x3fb8aa3b, v5
	v_exp_f32_e32 v5, v5
	v_cmp_gt_f32_e32 vcc, s34, v3
	v_mul_f32_e32 v4, v5, v4
	v_bfe_u32 v5, v4, 16, 1
	v_add3_u32 v4, v4, v5, s39
	v_mul_f32_e32 v5, 0xbfb8aa3b, v1
	v_exp_f32_e32 v5, v5
	ds_write_b16_d16_hi v2, v4 offset:1904
	v_sub_f32_e32 v4, 1.0, v3
	v_mul_f32_e32 v4, v5, v4
	v_bfe_u32 v5, v4, 16, 1
	v_add3_u32 v4, v4, v5, s39
	ds_write_b16_d16_hi v2, v4 offset:19312
	v_cndmask_b32_e64 v4, 0, 32, vcc
	v_ldexp_f32 v3, v3, v4
	v_log_f32_e32 v3, v3
	s_nop 0
	v_mul_f32_e32 v4, 0x3f317217, v3
	v_fma_f32 v4, v3, s38, -v4
	v_fmac_f32_e32 v4, 0x3377d1cf, v3
	v_fmac_f32_e32 v4, 0x3f317217, v3
	v_cmp_lt_f32_e64 s[82:83], |v3|, s20
	s_nop 1
	v_cndmask_b32_e64 v3, v3, v4, s[82:83]
	v_cndmask_b32_e32 v4, 0, v193, vcc
	v_sub_f32_e32 v3, v3, v4
	v_sub_f32_e32 v1, v1, v3
	v_mov_b32_e32 v3, v230
	v_lshlrev_b32_e32 v3, 16, v3
	v_mul_f32_e32 v3, 0xbfb8aa3b, v3
	v_exp_f32_e32 v3, v3
	s_nop 0
	v_add_f32_e32 v3, 1.0, v3
	v_div_scale_f32 v4, s[56:57], v3, v3, 1.0
	v_rcp_f32_e32 v5, v4
	s_nop 0
	v_fma_f32 v6, -v4, v5, 1.0
	v_fmac_f32_e32 v5, v6, v5
	v_div_scale_f32 v6, vcc, 1.0, v3, 1.0
	v_mul_f32_e32 v7, v6, v5
	v_fma_f32 v8, -v4, v7, v6
	v_fmac_f32_e32 v7, v8, v5
	v_fma_f32 v4, -v4, v7, v6
	v_div_fmas_f32 v4, v4, v5, v7
	v_div_fixup_f32 v3, v4, v3, 1.0
	v_mov_b32_e32 v4, v231
	v_fma_f32 v3, v0, v3, v58
	v_lshlrev_b32_e32 v4, 16, v4
	v_mul_f32_e32 v5, 0xbfb8aa3b, v4
	v_exp_f32_e32 v5, v5
	s_nop 0
	v_add_f32_e32 v5, 1.0, v5
	v_div_scale_f32 v6, s[56:57], v5, v5, v4
	v_rcp_f32_e32 v7, v6
	s_nop 0
	v_fma_f32 v8, -v6, v7, 1.0
	v_fmac_f32_e32 v7, v8, v7
	v_div_scale_f32 v8, vcc, v4, v5, v4
	v_mul_f32_e32 v9, v8, v7
	v_fma_f32 v10, -v6, v9, v8
	v_fmac_f32_e32 v9, v10, v7
	v_fma_f32 v6, -v6, v9, v8
	v_div_fmas_f32 v6, v6, v7, v9
	v_div_fixup_f32 v4, v6, v5, v4
	v_min_f32_e32 v5, 0x42a00000, v1
	v_mul_f32_e32 v5, 0x3fb8aa3b, v5
	v_exp_f32_e32 v5, v5
	v_cmp_gt_f32_e32 vcc, s34, v3
	v_mul_f32_e32 v4, v5, v4
	v_bfe_u32 v5, v4, 16, 1
	v_add3_u32 v4, v4, v5, s39
	v_mul_f32_e32 v5, 0xbfb8aa3b, v1
	v_exp_f32_e32 v5, v5
	ds_write_b16_d16_hi v2, v4 offset:1632
	v_sub_f32_e32 v4, 1.0, v3
	v_mul_f32_e32 v4, v5, v4
	v_bfe_u32 v5, v4, 16, 1
	v_add3_u32 v4, v4, v5, s39
	ds_write_b16_d16_hi v2, v4 offset:19040
	v_cndmask_b32_e64 v4, 0, 32, vcc
	v_ldexp_f32 v3, v3, v4
	v_log_f32_e32 v3, v3
	s_nop 0
	v_mul_f32_e32 v4, 0x3f317217, v3
	v_fma_f32 v4, v3, s38, -v4
	v_fmac_f32_e32 v4, 0x3377d1cf, v3
	v_fmac_f32_e32 v4, 0x3f317217, v3
	v_cmp_lt_f32_e64 s[82:83], |v3|, s20
	s_nop 1
	v_cndmask_b32_e64 v3, v3, v4, s[82:83]
	v_cndmask_b32_e32 v4, 0, v193, vcc
	v_sub_f32_e32 v3, v3, v4
	v_sub_f32_e32 v1, v1, v3
	v_mov_b32_e32 v3, v232
	v_lshlrev_b32_e32 v3, 16, v3
	v_mul_f32_e32 v3, 0xbfb8aa3b, v3
	v_exp_f32_e32 v3, v3
	s_nop 0
	v_add_f32_e32 v3, 1.0, v3
	v_div_scale_f32 v4, s[56:57], v3, v3, 1.0
	v_rcp_f32_e32 v5, v4
	s_nop 0
	v_fma_f32 v6, -v4, v5, 1.0
	v_fmac_f32_e32 v5, v6, v5
	v_div_scale_f32 v6, vcc, 1.0, v3, 1.0
	v_mul_f32_e32 v7, v6, v5
	v_fma_f32 v8, -v4, v7, v6
	v_fmac_f32_e32 v7, v8, v5
	v_fma_f32 v4, -v4, v7, v6
	v_div_fmas_f32 v4, v4, v5, v7
	v_div_fixup_f32 v3, v4, v3, 1.0
	v_mov_b32_e32 v4, v233
	v_fma_f32 v3, v0, v3, v58
	v_lshlrev_b32_e32 v4, 16, v4
	v_mul_f32_e32 v5, 0xbfb8aa3b, v4
	v_exp_f32_e32 v5, v5
	s_nop 0
	v_add_f32_e32 v5, 1.0, v5
	v_div_scale_f32 v6, s[56:57], v5, v5, v4
	v_rcp_f32_e32 v7, v6
	s_nop 0
	v_fma_f32 v8, -v6, v7, 1.0
	v_fmac_f32_e32 v7, v8, v7
; DEVI float b2f(bfu b) { return __uint_as_float(((unsigned)b) << 16); }
; DEVI float sigmoidf_(float x) { return 1.f / (1.f + __expf(-x)); }
; DEVI float siluf_(float x) { return x / (1.f + __expf(-x)); }
; DEVI void h3_item(const Params& P, int l, int ck, int h, char* smem, int tid) {
;     ...
; #pragma unroll 8
;     for (int t = Lh - 1; t >= 0; --t) {
;       float f = lb + (1.f - lb) * sigmoidf_(b2f(KT[t * 136 + d]));
;       float q = siluf_(b2f(QT[t * 136 + d]));
;       QT[t * 136 + d] = f2b(q * __expf(fminf(rel, 80.f)));
;       KT[t * 136 + d] = f2b((1.f - f) * __expf(-rel));
;       rel -= __logf(f);
;     }
	v_div_scale_f32 v8, vcc, v4, v5, v4
	v_mul_f32_e32 v9, v8, v7
	v_fma_f32 v10, -v6, v9, v8
	v_fmac_f32_e32 v9, v10, v7
	v_fma_f32 v6, -v6, v9, v8
	v_div_fmas_f32 v6, v6, v7, v9
	v_div_fixup_f32 v4, v6, v5, v4
	v_min_f32_e32 v5, 0x42a00000, v1
	v_mul_f32_e32 v5, 0x3fb8aa3b, v5
	v_exp_f32_e32 v5, v5
	v_cmp_gt_f32_e32 vcc, s34, v3
	v_mul_f32_e32 v4, v5, v4
	v_bfe_u32 v5, v4, 16, 1
	v_add3_u32 v4, v4, v5, s39
	v_mul_f32_e32 v5, 0xbfb8aa3b, v1
	v_exp_f32_e32 v5, v5
	ds_write_b16_d16_hi v2, v4 offset:1360
	v_sub_f32_e32 v4, 1.0, v3
	v_mul_f32_e32 v4, v5, v4
	v_bfe_u32 v5, v4, 16, 1
	v_add3_u32 v4, v4, v5, s39
	ds_write_b16_d16_hi v2, v4 offset:18768
	v_cndmask_b32_e64 v4, 0, 32, vcc
	v_ldexp_f32 v3, v3, v4
	v_log_f32_e32 v3, v3
	s_nop 0
	v_mul_f32_e32 v4, 0x3f317217, v3
	v_fma_f32 v4, v3, s38, -v4
	v_fmac_f32_e32 v4, 0x3377d1cf, v3
	v_fmac_f32_e32 v4, 0x3f317217, v3
	v_cmp_lt_f32_e64 s[82:83], |v3|, s20
	s_nop 1
	v_cndmask_b32_e64 v3, v3, v4, s[82:83]
	v_cndmask_b32_e32 v4, 0, v193, vcc
	v_sub_f32_e32 v3, v3, v4
	v_sub_f32_e32 v1, v1, v3
	v_mov_b32_e32 v3, v234
	v_lshlrev_b32_e32 v3, 16, v3
	v_mul_f32_e32 v3, 0xbfb8aa3b, v3
	v_exp_f32_e32 v3, v3
	s_nop 0
	v_add_f32_e32 v3, 1.0, v3
	v_div_scale_f32 v4, s[56:57], v3, v3, 1.0
	v_rcp_f32_e32 v5, v4
	s_nop 0
	v_fma_f32 v6, -v4, v5, 1.0
	v_fmac_f32_e32 v5, v6, v5
	v_div_scale_f32 v6, vcc, 1.0, v3, 1.0
	v_mul_f32_e32 v7, v6, v5
	v_fma_f32 v8, -v4, v7, v6
	v_fmac_f32_e32 v7, v8, v5
	v_fma_f32 v4, -v4, v7, v6
	v_div_fmas_f32 v4, v4, v5, v7
	v_div_fixup_f32 v3, v4, v3, 1.0
	v_mov_b32_e32 v4, v235
	v_fma_f32 v3, v0, v3, v58
	v_lshlrev_b32_e32 v4, 16, v4
	v_mul_f32_e32 v5, 0xbfb8aa3b, v4
	v_exp_f32_e32 v5, v5
	s_nop 0
	v_add_f32_e32 v5, 1.0, v5
	v_div_scale_f32 v6, s[56:57], v5, v5, v4
	v_rcp_f32_e32 v7, v6
	s_nop 0
	v_fma_f32 v8, -v6, v7, 1.0
	v_fmac_f32_e32 v7, v8, v7
	v_div_scale_f32 v8, vcc, v4, v5, v4
	v_mul_f32_e32 v9, v8, v7
	v_fma_f32 v10, -v6, v9, v8
	v_fmac_f32_e32 v9, v10, v7
	v_fma_f32 v6, -v6, v9, v8
	v_div_fmas_f32 v6, v6, v7, v9
	v_div_fixup_f32 v4, v6, v5, v4
	v_min_f32_e32 v5, 0x42a00000, v1
	v_mul_f32_e32 v5, 0x3fb8aa3b, v5
	v_exp_f32_e32 v5, v5
	v_cmp_gt_f32_e32 vcc, s34, v3
	v_mul_f32_e32 v4, v5, v4
	v_bfe_u32 v5, v4, 16, 1
	v_add3_u32 v4, v4, v5, s39
	v_mul_f32_e32 v5, 0xbfb8aa3b, v1
	v_exp_f32_e32 v5, v5
	ds_write_b16_d16_hi v2, v4 offset:1088
	v_sub_f32_e32 v4, 1.0, v3
	v_mul_f32_e32 v4, v5, v4
	v_bfe_u32 v5, v4, 16, 1
	v_add3_u32 v4, v4, v5, s39
	ds_write_b16_d16_hi v2, v4 offset:18496
	v_cndmask_b32_e64 v4, 0, 32, vcc
	v_ldexp_f32 v3, v3, v4
	v_log_f32_e32 v3, v3
	s_nop 0
	v_mul_f32_e32 v4, 0x3f317217, v3
	v_fma_f32 v4, v3, s38, -v4
	v_fmac_f32_e32 v4, 0x3377d1cf, v3
	v_fmac_f32_e32 v4, 0x3f317217, v3
	v_cmp_lt_f32_e64 s[82:83], |v3|, s20
	s_nop 1
	v_cndmask_b32_e64 v3, v3, v4, s[82:83]
	v_cndmask_b32_e32 v4, 0, v193, vcc
	v_sub_f32_e32 v3, v3, v4
	v_sub_f32_e32 v1, v1, v3
	v_mov_b32_e32 v3, v236
	v_lshlrev_b32_e32 v3, 16, v3
	v_mul_f32_e32 v3, 0xbfb8aa3b, v3
	v_exp_f32_e32 v3, v3
	s_nop 0
	v_add_f32_e32 v3, 1.0, v3
	v_div_scale_f32 v4, s[56:57], v3, v3, 1.0
	v_rcp_f32_e32 v5, v4
	s_nop 0
	v_fma_f32 v6, -v4, v5, 1.0
	v_fmac_f32_e32 v5, v6, v5
	v_div_scale_f32 v6, vcc, 1.0, v3, 1.0
	v_mul_f32_e32 v7, v6, v5
	v_fma_f32 v8, -v4, v7, v6
	v_fmac_f32_e32 v7, v8, v5
	v_fma_f32 v4, -v4, v7, v6
	v_div_fmas_f32 v4, v4, v5, v7
	v_div_fixup_f32 v3, v4, v3, 1.0
	v_mov_b32_e32 v4, v237
	v_fma_f32 v3, v0, v3, v58
	v_lshlrev_b32_e32 v4, 16, v4
	v_mul_f32_e32 v5, 0xbfb8aa3b, v4
	v_exp_f32_e32 v5, v5
	s_nop 0
	v_add_f32_e32 v5, 1.0, v5
	v_div_scale_f32 v6, s[56:57], v5, v5, v4
	v_rcp_f32_e32 v7, v6
	s_nop 0
	v_fma_f32 v8, -v6, v7, 1.0
	v_fmac_f32_e32 v7, v8, v7
	v_div_scale_f32 v8, vcc, v4, v5, v4
	v_mul_f32_e32 v9, v8, v7
	v_fma_f32 v10, -v6, v9, v8
	v_fmac_f32_e32 v9, v10, v7
	v_fma_f32 v6, -v6, v9, v8
	v_div_fmas_f32 v6, v6, v7, v9
	v_div_fixup_f32 v4, v6, v5, v4
	v_min_f32_e32 v5, 0x42a00000, v1
	v_mul_f32_e32 v5, 0x3fb8aa3b, v5
	v_exp_f32_e32 v5, v5
	v_cmp_gt_f32_e32 vcc, s34, v3
	v_mul_f32_e32 v4, v5, v4
	v_bfe_u32 v5, v4, 16, 1
	v_add3_u32 v4, v4, v5, s39
	v_mul_f32_e32 v5, 0xbfb8aa3b, v1
	v_exp_f32_e32 v5, v5
	ds_write_b16_d16_hi v2, v4 offset:816
	v_sub_f32_e32 v4, 1.0, v3
	v_mul_f32_e32 v4, v5, v4
	v_bfe_u32 v5, v4, 16, 1
	v_add3_u32 v4, v4, v5, s39
	ds_write_b16_d16_hi v2, v4 offset:18224
	v_cndmask_b32_e64 v4, 0, 32, vcc
	v_ldexp_f32 v3, v3, v4
	v_log_f32_e32 v3, v3
	s_nop 0
	v_mul_f32_e32 v4, 0x3f317217, v3
	v_fma_f32 v4, v3, s38, -v4
	v_fmac_f32_e32 v4, 0x3377d1cf, v3
	v_fmac_f32_e32 v4, 0x3f317217, v3
	v_cmp_lt_f32_e64 s[82:83], |v3|, s20
	s_nop 1
	v_cndmask_b32_e64 v3, v3, v4, s[82:83]
	v_cndmask_b32_e32 v4, 0, v193, vcc
	v_sub_f32_e32 v3, v3, v4
	v_sub_f32_e32 v1, v1, v3
	v_mov_b32_e32 v3, v238
	v_lshlrev_b32_e32 v3, 16, v3
	v_mul_f32_e32 v3, 0xbfb8aa3b, v3
	v_exp_f32_e32 v3, v3
	s_nop 0
	v_add_f32_e32 v3, 1.0, v3
	v_div_scale_f32 v4, s[56:57], v3, v3, 1.0
	v_rcp_f32_e32 v5, v4
	s_nop 0
	v_fma_f32 v6, -v4, v5, 1.0
	v_fmac_f32_e32 v5, v6, v5
	v_div_scale_f32 v6, vcc, 1.0, v3, 1.0
	v_mul_f32_e32 v7, v6, v5
	v_fma_f32 v8, -v4, v7, v6
	v_fmac_f32_e32 v7, v8, v5
	v_fma_f32 v4, -v4, v7, v6
; DEVI float b2f(bfu b) { return __uint_as_float(((unsigned)b) << 16); }
; DEVI float sigmoidf_(float x) { return 1.f / (1.f + __expf(-x)); }
; DEVI float siluf_(float x) { return x / (1.f + __expf(-x)); }
; DEVI void h3_item(const Params& P, int l, int ck, int h, char* smem, int tid) {
;     ...
; #pragma unroll 8
;     for (int t = Lh - 1; t >= 0; --t) {
;       float f = lb + (1.f - lb) * sigmoidf_(b2f(KT[t * 136 + d]));
;       float q = siluf_(b2f(QT[t * 136 + d]));
;       QT[t * 136 + d] = f2b(q * __expf(fminf(rel, 80.f)));
;       KT[t * 136 + d] = f2b((1.f - f) * __expf(-rel));
;       rel -= __logf(f);
;     }
;     bmid[d] = -rel;
	v_div_fmas_f32 v4, v4, v5, v7
	v_div_fixup_f32 v3, v4, v3, 1.0
	v_mov_b32_e32 v4, v239
	v_fma_f32 v3, v0, v3, v58
	v_lshlrev_b32_e32 v4, 16, v4
	v_mul_f32_e32 v5, 0xbfb8aa3b, v4
	v_exp_f32_e32 v5, v5
	s_nop 0
	v_add_f32_e32 v5, 1.0, v5
	v_div_scale_f32 v6, s[56:57], v5, v5, v4
	v_rcp_f32_e32 v7, v6
	s_nop 0
	v_fma_f32 v8, -v6, v7, 1.0
	v_fmac_f32_e32 v7, v8, v7
	v_div_scale_f32 v8, vcc, v4, v5, v4
	v_mul_f32_e32 v9, v8, v7
	v_fma_f32 v10, -v6, v9, v8
	v_fmac_f32_e32 v9, v10, v7
	v_fma_f32 v6, -v6, v9, v8
	v_div_fmas_f32 v6, v6, v7, v9
	v_div_fixup_f32 v4, v6, v5, v4
	v_min_f32_e32 v5, 0x42a00000, v1
	v_mul_f32_e32 v5, 0x3fb8aa3b, v5
	v_exp_f32_e32 v5, v5
	v_cmp_gt_f32_e32 vcc, s34, v3
	v_mul_f32_e32 v4, v5, v4
	v_bfe_u32 v5, v4, 16, 1
	v_add3_u32 v4, v4, v5, s39
	v_mul_f32_e32 v5, 0xbfb8aa3b, v1
	v_exp_f32_e32 v5, v5
	ds_write_b16_d16_hi v2, v4 offset:544
	v_sub_f32_e32 v4, 1.0, v3
	v_mul_f32_e32 v4, v5, v4
	v_bfe_u32 v5, v4, 16, 1
	v_add3_u32 v4, v4, v5, s39
	ds_write_b16_d16_hi v2, v4 offset:17952
	v_cndmask_b32_e64 v4, 0, 32, vcc
	v_ldexp_f32 v3, v3, v4
	v_log_f32_e32 v3, v3
	s_nop 0
	v_mul_f32_e32 v4, 0x3f317217, v3
	v_fma_f32 v4, v3, s38, -v4
	v_fmac_f32_e32 v4, 0x3377d1cf, v3
	v_fmac_f32_e32 v4, 0x3f317217, v3
	v_cmp_lt_f32_e64 s[82:83], |v3|, s20
	s_nop 1
	v_cndmask_b32_e64 v3, v3, v4, s[82:83]
	v_cndmask_b32_e32 v4, 0, v193, vcc
	v_sub_f32_e32 v3, v3, v4
	v_sub_f32_e32 v1, v1, v3
	v_mov_b32_e32 v3, v240
	v_lshlrev_b32_e32 v3, 16, v3
	v_mul_f32_e32 v3, 0xbfb8aa3b, v3
	v_exp_f32_e32 v3, v3
	s_nop 0
	v_add_f32_e32 v3, 1.0, v3
	v_div_scale_f32 v4, s[56:57], v3, v3, 1.0
	v_rcp_f32_e32 v5, v4
	s_nop 0
	v_fma_f32 v6, -v4, v5, 1.0
	v_fmac_f32_e32 v5, v6, v5
	v_div_scale_f32 v6, vcc, 1.0, v3, 1.0
	v_mul_f32_e32 v7, v6, v5
	v_fma_f32 v8, -v4, v7, v6
	v_fmac_f32_e32 v7, v8, v5
	v_fma_f32 v4, -v4, v7, v6
	v_div_fmas_f32 v4, v4, v5, v7
	v_div_fixup_f32 v3, v4, v3, 1.0
	v_mov_b32_e32 v4, v241
	v_fma_f32 v3, v0, v3, v58
	v_lshlrev_b32_e32 v4, 16, v4
	v_mul_f32_e32 v5, 0xbfb8aa3b, v4
	v_exp_f32_e32 v5, v5
	s_nop 0
	v_add_f32_e32 v5, 1.0, v5
	v_div_scale_f32 v6, s[56:57], v5, v5, v4
	v_rcp_f32_e32 v7, v6
	s_nop 0
	v_fma_f32 v8, -v6, v7, 1.0
	v_fmac_f32_e32 v7, v8, v7
	v_div_scale_f32 v8, vcc, v4, v5, v4
	v_mul_f32_e32 v9, v8, v7
	v_fma_f32 v10, -v6, v9, v8
	v_fmac_f32_e32 v9, v10, v7
	v_fma_f32 v6, -v6, v9, v8
	v_div_fmas_f32 v6, v6, v7, v9
	v_div_fixup_f32 v4, v6, v5, v4
	v_min_f32_e32 v5, 0x42a00000, v1
	v_mul_f32_e32 v5, 0x3fb8aa3b, v5
	v_exp_f32_e32 v5, v5
	v_cmp_gt_f32_e32 vcc, s34, v3
	v_mul_f32_e32 v4, v5, v4
	v_bfe_u32 v5, v4, 16, 1
	v_add3_u32 v4, v4, v5, s39
	v_mul_f32_e32 v5, 0xbfb8aa3b, v1
	v_exp_f32_e32 v5, v5
	ds_write_b16_d16_hi v2, v4 offset:272
	v_sub_f32_e32 v4, 1.0, v3
	v_mul_f32_e32 v4, v5, v4
	v_bfe_u32 v5, v4, 16, 1
	v_add3_u32 v4, v4, v5, s39
	ds_write_b16_d16_hi v2, v4 offset:17680
	v_cndmask_b32_e64 v4, 0, 32, vcc
	v_ldexp_f32 v3, v3, v4
	v_log_f32_e32 v3, v3
	s_nop 0
	v_mul_f32_e32 v4, 0x3f317217, v3
	v_fma_f32 v4, v3, s38, -v4
	v_fmac_f32_e32 v4, 0x3377d1cf, v3
	v_fmac_f32_e32 v4, 0x3f317217, v3
	v_cmp_lt_f32_e64 s[82:83], |v3|, s20
	s_nop 1
	v_cndmask_b32_e64 v3, v3, v4, s[82:83]
	v_cndmask_b32_e32 v4, 0, v193, vcc
	v_sub_f32_e32 v3, v3, v4
	v_sub_f32_e32 v1, v1, v3
	v_mov_b32_e32 v3, v242
	v_lshlrev_b32_e32 v3, 16, v3
	v_mul_f32_e32 v3, 0xbfb8aa3b, v3
	v_exp_f32_e32 v3, v3
	s_nop 0
	v_add_f32_e32 v3, 1.0, v3
	v_div_scale_f32 v4, s[56:57], v3, v3, 1.0
	v_rcp_f32_e32 v5, v4
	s_nop 0
	v_fma_f32 v6, -v4, v5, 1.0
	v_fmac_f32_e32 v5, v6, v5
	v_div_scale_f32 v6, vcc, 1.0, v3, 1.0
	v_mul_f32_e32 v7, v6, v5
	v_fma_f32 v8, -v4, v7, v6
	v_fmac_f32_e32 v7, v8, v5
	v_fma_f32 v4, -v4, v7, v6
	v_div_fmas_f32 v4, v4, v5, v7
	v_div_fixup_f32 v3, v4, v3, 1.0
	v_mov_b32_e32 v4, v243
	v_fma_f32 v3, v0, v3, v58
	v_lshlrev_b32_e32 v4, 16, v4
	v_mul_f32_e32 v5, 0xbfb8aa3b, v4
	v_exp_f32_e32 v5, v5
	s_nop 0
	v_add_f32_e32 v5, 1.0, v5
	v_div_scale_f32 v6, s[56:57], v5, v5, v4
	v_rcp_f32_e32 v7, v6
	s_nop 0
	v_fma_f32 v8, -v6, v7, 1.0
	v_fmac_f32_e32 v7, v8, v7
	v_div_scale_f32 v8, vcc, v4, v5, v4
	v_mul_f32_e32 v9, v8, v7
	v_fma_f32 v10, -v6, v9, v8
	v_fmac_f32_e32 v9, v10, v7
	v_fma_f32 v6, -v6, v9, v8
	v_div_fmas_f32 v6, v6, v7, v9
	v_div_fixup_f32 v4, v6, v5, v4
	v_min_f32_e32 v5, 0x42a00000, v1
	v_mul_f32_e32 v5, 0x3fb8aa3b, v5
	v_exp_f32_e32 v5, v5
	v_cmp_gt_f32_e32 vcc, s34, v3
	v_mul_f32_e32 v4, v5, v4
	v_bfe_u32 v5, v4, 16, 1
	v_add3_u32 v4, v4, v5, s39
	v_mul_f32_e32 v5, 0xbfb8aa3b, v1
	v_exp_f32_e32 v5, v5
	ds_write_b16_d16_hi v2, v4
	v_sub_f32_e32 v4, 1.0, v3
	v_mul_f32_e32 v4, v5, v4
	v_bfe_u32 v5, v4, 16, 1
	v_add3_u32 v4, v4, v5, s39
	ds_write_b16_d16_hi v2, v4 offset:17408
	v_cndmask_b32_e64 v2, 0, 32, vcc
	v_ldexp_f32 v2, v3, v2
	v_log_f32_e32 v2, v2
	s_nop 0
	v_mul_f32_e32 v3, 0x3f317217, v2
	v_fma_f32 v3, v2, s38, -v3
	v_fmac_f32_e32 v3, 0x3377d1cf, v2
	v_fmac_f32_e32 v3, 0x3f317217, v2
	v_cmp_lt_f32_e64 s[82:83], |v2|, s20
	s_nop 1
	v_cndmask_b32_e64 v2, v2, v3, s[82:83]
	v_cndmask_b32_e32 v3, 0, v193, vcc
	v_sub_f32_e32 v2, v2, v3
	v_sub_f32_e32 v1, v1, v2
	s_cbranch_scc0 .LBB0_556
	v_xor_b32_e32 v0, 0x80000000, v1
	ds_write_b32 v199, v0 offset:62464
